# attention-phase preamble: 8-iteration max|gain| load loop issued as one 32-load batch; on top of v61 (hyena interleaved loads, tile-local final, attention back-edge rotation)
# baseline (speedup 1.0000x reference)
; __device__ __forceinline__ void phase_attn(int l, char* lds_generic, int vcu, int G) {
;     ...
;     float bA, bC;
;     { float gq = 0.f, gk = 0.f, cq = 0.f, ck = 0.f;
;       for (int i = 0; i < 64; ++i) { gq = fmaxf(gq, fabsf(P->in[7][l * 64 + i])); gk = fmaxf(gk, fabsf(P->in[8][l * 64 + i])); }
;       for (int i = 0; i < 32; ++i) { cq = fmaxf(cq, fabsf(P->in[18][l * 32 + i])); ck = fmaxf(ck, fabsf(P->in[19][l * 32 + i])); }
;       bA = 64.f * 0.125f * 1.4426950408889634f * 1.03f * gq * gk; bC = 32.f * 0.17677669529663687f * 1.4426950408889634f * 1.03f * cq * ck; }
;     const bool fix = (bA < 40.f) && (bC < 40.f);
.LBB0_329:
	global_load_dwordx4 v[4:7], v1, s[2:3]
	global_load_dwordx4 v[8:11], v1, s[2:3] offset:16
	global_load_dwordx4 v[12:15], v1, s[2:3] offset:32
	global_load_dwordx4 v[16:19], v1, s[2:3] offset:48
	global_load_dwordx4 v[20:23], v1, s[2:3] offset:64
	global_load_dwordx4 v[24:27], v1, s[2:3] offset:80
	global_load_dwordx4 v[28:31], v1, s[2:3] offset:96
	global_load_dwordx4 v[32:35], v1, s[2:3] offset:112
	global_load_dwordx4 v[36:39], v1, s[2:3] offset:128
	global_load_dwordx4 v[40:43], v1, s[2:3] offset:144
	global_load_dwordx4 v[44:47], v1, s[2:3] offset:160
	global_load_dwordx4 v[48:51], v1, s[2:3] offset:176
	global_load_dwordx4 v[52:55], v1, s[2:3] offset:192
	global_load_dwordx4 v[56:59], v1, s[2:3] offset:208
	global_load_dwordx4 v[60:63], v1, s[2:3] offset:224
	global_load_dwordx4 v[64:67], v1, s[2:3] offset:240
	global_load_dwordx4 v[68:71], v1, s[14:15]
	global_load_dwordx4 v[72:75], v1, s[14:15] offset:16
	global_load_dwordx4 v[76:79], v1, s[14:15] offset:32
	global_load_dwordx4 v[80:83], v1, s[14:15] offset:48
	global_load_dwordx4 v[84:87], v1, s[14:15] offset:64
	global_load_dwordx4 v[88:91], v1, s[14:15] offset:80
	global_load_dwordx4 v[92:95], v1, s[14:15] offset:96
	global_load_dwordx4 v[96:99], v1, s[14:15] offset:112
	global_load_dwordx4 v[100:103], v1, s[14:15] offset:128
	global_load_dwordx4 v[104:107], v1, s[14:15] offset:144
	global_load_dwordx4 v[108:111], v1, s[14:15] offset:160
	global_load_dwordx4 v[112:115], v1, s[14:15] offset:176
	global_load_dwordx4 v[116:119], v1, s[14:15] offset:192
	global_load_dwordx4 v[120:123], v1, s[14:15] offset:208
	global_load_dwordx4 v[124:127], v1, s[14:15] offset:224
	global_load_dwordx4 v[128:131], v1, s[14:15] offset:240
	s_waitcnt vmcnt(16)
	v_max3_f32 v2, v2, |v4|, |v5|
	v_max3_f32 v2, v2, |v6|, |v7|
	v_max3_f32 v2, v2, |v8|, |v9|
	v_max3_f32 v2, v2, |v10|, |v11|
	v_max3_f32 v2, v2, |v12|, |v13|
	v_max3_f32 v2, v2, |v14|, |v15|
	v_max3_f32 v2, v2, |v16|, |v17|
	v_max3_f32 v2, v2, |v18|, |v19|
	v_max3_f32 v2, v2, |v20|, |v21|
	v_max3_f32 v2, v2, |v22|, |v23|
	v_max3_f32 v2, v2, |v24|, |v25|
	v_max3_f32 v2, v2, |v26|, |v27|
	v_max3_f32 v2, v2, |v28|, |v29|
	v_max3_f32 v2, v2, |v30|, |v31|
	v_max3_f32 v2, v2, |v32|, |v33|
	v_max3_f32 v2, v2, |v34|, |v35|
	v_max3_f32 v2, v2, |v36|, |v37|
	v_max3_f32 v2, v2, |v38|, |v39|
	v_max3_f32 v2, v2, |v40|, |v41|
	v_max3_f32 v2, v2, |v42|, |v43|
	v_max3_f32 v2, v2, |v44|, |v45|
	v_max3_f32 v2, v2, |v46|, |v47|
	v_max3_f32 v2, v2, |v48|, |v49|
	v_max3_f32 v2, v2, |v50|, |v51|
	v_max3_f32 v2, v2, |v52|, |v53|
	v_max3_f32 v2, v2, |v54|, |v55|
	v_max3_f32 v2, v2, |v56|, |v57|
	v_max3_f32 v2, v2, |v58|, |v59|
	v_max3_f32 v2, v2, |v60|, |v61|
	v_max3_f32 v2, v2, |v62|, |v63|
	v_max3_f32 v2, v2, |v64|, |v65|
	v_max3_f32 v2, v2, |v66|, |v67|
	s_waitcnt vmcnt(0)
	v_max3_f32 v0, v0, |v68|, |v69|
	v_max3_f32 v0, v0, |v70|, |v71|
	v_max3_f32 v0, v0, |v72|, |v73|
	v_max3_f32 v0, v0, |v74|, |v75|
	v_max3_f32 v0, v0, |v76|, |v77|
	v_max3_f32 v0, v0, |v78|, |v79|
	v_max3_f32 v0, v0, |v80|, |v81|
	v_max3_f32 v0, v0, |v82|, |v83|
	v_max3_f32 v0, v0, |v84|, |v85|
	v_max3_f32 v0, v0, |v86|, |v87|
	v_max3_f32 v0, v0, |v88|, |v89|
	v_max3_f32 v0, v0, |v90|, |v91|
	v_max3_f32 v0, v0, |v92|, |v93|
	v_max3_f32 v0, v0, |v94|, |v95|
	v_max3_f32 v0, v0, |v96|, |v97|
	v_max3_f32 v0, v0, |v98|, |v99|
	v_max3_f32 v0, v0, |v100|, |v101|
	v_max3_f32 v0, v0, |v102|, |v103|
	v_max3_f32 v0, v0, |v104|, |v105|
	v_max3_f32 v0, v0, |v106|, |v107|
	v_max3_f32 v0, v0, |v108|, |v109|
	v_max3_f32 v0, v0, |v110|, |v111|
	v_max3_f32 v0, v0, |v112|, |v113|
	v_max3_f32 v0, v0, |v114|, |v115|
	v_max3_f32 v0, v0, |v116|, |v117|
	v_max3_f32 v0, v0, |v118|, |v119|
	v_max3_f32 v0, v0, |v120|, |v121|
	v_max3_f32 v0, v0, |v122|, |v123|
	v_max3_f32 v0, v0, |v124|, |v125|
	v_max3_f32 v0, v0, |v126|, |v127|
	v_max3_f32 v0, v0, |v128|, |v129|
	v_max3_f32 v0, v0, |v130|, |v131|
	s_load_dwordx8 s[40:47], s[0:1], 0x90
	s_load_dwordx4 s[48:51], s[0:1], 0xb0
	s_load_dwordx2 s[60:61], s[0:1], 0xc0
	s_lshl_b64 s[58:59], s[58:59], 2
	v_mul_f32_e32 v66, 0x413e3475, v2
	s_waitcnt lgkmcnt(0)
	s_add_u32 s2, s40, s58
	s_addc_u32 s3, s41, s59
	s_add_u32 s14, s42, s58
	s_addc_u32 s15, s43, s59
	global_load_dwordx4 v[4:7], v1, s[2:3] offset:48
	global_load_dwordx4 v[8:11], v1, s[2:3] offset:32
	global_load_dwordx4 v[12:15], v1, s[2:3] offset:16
	global_load_dwordx4 v[16:19], v1, s[2:3]
	global_load_dwordx4 v[20:23], v1, s[14:15] offset:48
	global_load_dwordx4 v[24:27], v1, s[14:15] offset:32
	global_load_dwordx4 v[28:31], v1, s[14:15] offset:16
	global_load_dwordx4 v[32:35], v1, s[14:15]
	s_add_u32 s40, s44, s58
	s_addc_u32 s41, s45, s59
	s_add_u32 s42, s46, s58
	s_addc_u32 s43, s47, s59
	s_add_u32 s46, s48, s58
	s_addc_u32 s47, s49, s59
	s_add_u32 s44, s50, s58
	s_addc_u32 s45, s51, s59
	v_mul_f32_e32 v212, v0, v66
	s_waitcnt vmcnt(4)
	v_max3_f32 v3, |v16|, 0, |v17|
	s_waitcnt vmcnt(0)
	v_max3_f32 v16, |v32|, 0, |v33|
	v_max3_f32 v3, v3, |v18|, |v19|
	v_max3_f32 v16, v16, |v34|, |v35|
	v_max3_f32 v3, v3, |v12|, |v13|
	v_max3_f32 v12, v16, |v28|, |v29|
	v_max3_f32 v3, v3, |v14|, |v15|
	v_max3_f32 v12, v12, |v30|, |v31|
	v_max3_f32 v3, v3, |v8|, |v9|
	v_max3_f32 v8, v12, |v24|, |v25|
	v_max3_f32 v3, v3, |v10|, |v11|
	v_max3_f32 v8, v8, |v26|, |v27|
	v_max3_f32 v3, v3, |v4|, |v5|
	v_max3_f32 v4, v8, |v20|, |v21|
	v_max3_f32 v3, v3, |v6|, |v7|
	v_max3_f32 v36, v4, |v22|, |v23|
	global_load_dwordx4 v[4:7], v1, s[2:3] offset:112
	global_load_dwordx4 v[8:11], v1, s[2:3] offset:96
	global_load_dwordx4 v[12:15], v1, s[2:3] offset:80
	global_load_dwordx4 v[16:19], v1, s[2:3] offset:64
	global_load_dwordx4 v[20:23], v1, s[14:15] offset:112
	global_load_dwordx4 v[24:27], v1, s[14:15] offset:96
	global_load_dwordx4 v[28:31], v1, s[14:15] offset:80
	global_load_dwordx4 v[32:35], v1, s[14:15] offset:64
	s_mov_b32 s2, 0x42200000
	s_mov_b32 s3, 0xc2ce8ed0
	s_mov_b32 s14, 0x42b17218
	s_waitcnt vmcnt(4)
; __device__ __forceinline__ void phase_attn(int l, char* lds_generic, int vcu, int G) {
;     ...
;       for (int i = 0; i < 32; ++i) { cq = fmaxf(cq, fabsf(P->in[18][l * 32 + i])); ck = fmaxf(ck, fabsf(P->in[19][l * 32 + i])); }
;       bA = 64.f * 0.125f * 1.4426950408889634f * 1.03f * gq * gk; bC = 32.f * 0.17677669529663687f * 1.4426950408889634f * 1.03f * cq * ck; }
;     const bool fix = (bA < 40.f) && (bC < 40.f);
;     float lam;
;     { float s1 = 0.f, s2 = 0.f;
;       for (int i = 0; i < 32; ++i) { s1 += P->in[20][l * 32 + i] * P->in[21][l * 32 + i]; s2 += P->in[22][l * 32 + i] * P->in[23][l * 32 + i]; }
;       lam = expf(s1) - expf(s2) + P->lam_init[l]; }
;     const float oml = 1.0f - P->lam_init[l]; const float* subln = P->in[24] + l * 64;
	v_max3_f32 v3, v3, |v16|, |v17|
	v_max3_f32 v3, v3, |v18|, |v19|
	v_max3_f32 v3, v3, |v12|, |v13|
	v_max3_f32 v3, v3, |v14|, |v15|
	s_waitcnt vmcnt(0)
	v_max3_f32 v16, v36, |v32|, |v33|
	v_max3_f32 v16, v16, |v34|, |v35|
	v_max3_f32 v12, v16, |v28|, |v29|
	v_max3_f32 v12, v12, |v30|, |v31|
	v_max3_f32 v3, v3, |v8|, |v9|
	v_max3_f32 v8, v12, |v24|, |v25|
	v_max3_f32 v3, v3, |v10|, |v11|
	v_max3_f32 v8, v8, |v26|, |v27|
	v_max3_f32 v3, v3, |v4|, |v5|
	v_max3_f32 v4, v8, |v20|, |v21|
	v_max3_f32 v3, v3, |v6|, |v7|
	v_max3_f32 v4, v4, |v22|, |v23|
	v_mul_f32_e32 v2, 0x41067ec4, v3
	v_mul_f32_e32 v207, v4, v2
	global_load_dwordx4 v[2:5], v1, s[40:41] offset:48
	global_load_dwordx4 v[6:9], v1, s[40:41] offset:32
	global_load_dwordx4 v[10:13], v1, s[40:41] offset:16
	global_load_dwordx4 v[14:17], v1, s[40:41]
	global_load_dwordx4 v[18:21], v1, s[42:43] offset:48
	global_load_dwordx4 v[22:25], v1, s[42:43] offset:32
	global_load_dwordx4 v[26:29], v1, s[42:43] offset:16
	global_load_dwordx4 v[30:33], v1, s[42:43]
	global_load_dwordx4 v[34:37], v1, s[46:47] offset:48
	global_load_dwordx4 v[38:41], v1, s[46:47] offset:32
	global_load_dwordx4 v[42:45], v1, s[46:47] offset:16
	global_load_dwordx4 v[46:49], v1, s[46:47]
	global_load_dwordx4 v[50:53], v1, s[44:45] offset:48
	global_load_dwordx4 v[54:57], v1, s[44:45] offset:32
	global_load_dwordx4 v[58:61], v1, s[44:45] offset:16
	global_load_dwordx4 v[62:65], v1, s[44:45]
	v_cmp_ngt_f32_e32 vcc, s2, v207
	s_waitcnt vmcnt(8)
	v_fma_f32 v67, v14, v30, 0
	v_fmac_f32_e32 v67, v15, v31
	v_fmac_f32_e32 v67, v16, v32
	v_fmac_f32_e32 v67, v17, v33
	s_waitcnt vmcnt(0)
	v_fma_f32 v68, v46, v62, 0
	v_fmac_f32_e32 v67, v10, v26
	v_fmac_f32_e32 v68, v47, v63
	v_fmac_f32_e32 v67, v11, v27
	v_fmac_f32_e32 v68, v48, v64
	v_fmac_f32_e32 v67, v12, v28
	v_fmac_f32_e32 v68, v49, v65
	v_fmac_f32_e32 v67, v13, v29
	v_fmac_f32_e32 v68, v42, v58
	v_fmac_f32_e32 v67, v6, v22
	v_fmac_f32_e32 v68, v43, v59
	v_fmac_f32_e32 v67, v7, v23
	v_fmac_f32_e32 v68, v44, v60
	v_fmac_f32_e32 v67, v8, v24
	v_fmac_f32_e32 v68, v45, v61
	v_fmac_f32_e32 v67, v9, v25
	v_fmac_f32_e32 v68, v38, v54
	v_fmac_f32_e32 v67, v2, v18
	v_fmac_f32_e32 v68, v39, v55
	v_fmac_f32_e32 v67, v3, v19
	v_fmac_f32_e32 v68, v40, v56
	v_fmac_f32_e32 v67, v4, v20
	v_fmac_f32_e32 v68, v41, v57
	v_fmac_f32_e32 v67, v5, v21
	global_load_dwordx4 v[2:5], v1, s[40:41] offset:112
	global_load_dwordx4 v[6:9], v1, s[40:41] offset:96
	global_load_dwordx4 v[10:13], v1, s[40:41] offset:80
	global_load_dwordx4 v[46:49], v1, s[40:41] offset:64
	global_load_dwordx4 v[14:17], v1, s[42:43] offset:112
	global_load_dwordx4 v[26:29], v1, s[42:43] offset:96
	global_load_dwordx4 v[38:41], v1, s[42:43] offset:80
	global_load_dwordx4 v[54:57], v1, s[42:43] offset:64
	v_fmac_f32_e32 v68, v34, v50
	v_fmac_f32_e32 v68, v35, v51
	v_fmac_f32_e32 v68, v36, v52
	v_fmac_f32_e32 v68, v37, v53
	global_load_dwordx4 v[18:21], v1, s[46:47] offset:112
	global_load_dwordx4 v[30:33], v1, s[46:47] offset:96
	global_load_dwordx4 v[42:45], v1, s[46:47] offset:80
	global_load_dwordx4 v[58:61], v1, s[46:47] offset:64
	global_load_dwordx4 v[22:25], v1, s[44:45] offset:112
	global_load_dwordx4 v[34:37], v1, s[44:45] offset:96
	global_load_dwordx4 v[50:53], v1, s[44:45] offset:80
	global_load_dwordx4 v[62:65], v1, s[44:45] offset:64
	v_cmp_ngt_f32_e64 s[40:41], s2, v212
	s_mov_b32 s2, 0x3fb8aa3b
	s_or_b64 s[40:41], s[40:41], vcc
	s_waitcnt vmcnt(8)
	v_fmac_f32_e32 v67, v46, v54
	v_fmac_f32_e32 v67, v47, v55
	v_fmac_f32_e32 v67, v48, v56
	v_fmac_f32_e32 v67, v49, v57
	v_fmac_f32_e32 v67, v10, v38
	v_fmac_f32_e32 v67, v11, v39
	v_fmac_f32_e32 v67, v12, v40
	v_fmac_f32_e32 v67, v13, v41
	s_waitcnt vmcnt(0)
	v_fmac_f32_e32 v68, v58, v62
	v_fmac_f32_e32 v67, v6, v26
	v_fmac_f32_e32 v68, v59, v63
	v_fmac_f32_e32 v67, v7, v27
	v_fmac_f32_e32 v68, v60, v64
	v_fmac_f32_e32 v67, v8, v28
	v_fmac_f32_e32 v68, v61, v65
	v_fmac_f32_e32 v67, v9, v29
	v_fmac_f32_e32 v68, v42, v50
	v_fmac_f32_e32 v67, v2, v14
	v_fmac_f32_e32 v68, v43, v51
	v_fmac_f32_e32 v67, v3, v15
	v_fmac_f32_e32 v68, v44, v52
	v_fmac_f32_e32 v67, v4, v16
	v_fmac_f32_e32 v68, v45, v53
	v_fmac_f32_e32 v67, v5, v17
	v_fmac_f32_e32 v68, v30, v34
	v_mul_f32_e32 v0, 0x3fb8aa3b, v67
	v_fmac_f32_e32 v68, v31, v35
	v_fma_f32 v2, v67, s2, -v0
	v_rndne_f32_e32 v3, v0
	v_fmac_f32_e32 v68, v32, v36
	v_fmac_f32_e32 v2, 0x32a5705f, v67
	v_sub_f32_e32 v0, v0, v3
	v_fmac_f32_e32 v68, v33, v37
	v_add_f32_e32 v0, v0, v2
	v_fmac_f32_e32 v68, v18, v22
	v_exp_f32_e32 v0, v0
	v_cvt_i32_f32_e32 v2, v3
	v_fmac_f32_e32 v68, v19, v23
	v_fmac_f32_e32 v68, v20, v24
	v_fmac_f32_e32 v68, v21, v25
	v_ldexp_f32 v0, v0, v2
	v_mul_f32_e32 v2, 0x3fb8aa3b, v68
	v_fma_f32 v3, v68, s2, -v2
	v_rndne_f32_e32 v4, v2
	v_cmp_ngt_f32_e32 vcc, s3, v67
	v_fmac_f32_e32 v3, 0x32a5705f, v68
	v_sub_f32_e32 v2, v2, v4
	v_cndmask_b32_e32 v0, 0, v0, vcc
	v_cmp_nlt_f32_e32 vcc, s14, v67
	v_add_f32_e32 v2, v2, v3
	v_exp_f32_e32 v2, v2
	v_cndmask_b32_e32 v0, v226, v0, vcc
	v_cvt_i32_f32_e32 v3, v4
	v_cmp_ngt_f32_e32 vcc, s3, v68
	s_lshl_b64 s[2:3], s[76:77], 2
	s_add_u32 s0, s0, s2
	s_addc_u32 s1, s1, s3
	s_load_dword s0, s[0:1], 0x120
	v_ldexp_f32 v2, v2, v3
	v_cndmask_b32_e32 v2, 0, v2, vcc
	v_cmp_nlt_f32_e32 vcc, s14, v68
	v_readlane_b32 s2, v247, 8
	s_waitcnt lgkmcnt(0)
	v_sub_f32_e64 v204, 1.0, s0
	v_cndmask_b32_e32 v2, v226, v2, vcc
	v_sub_f32_e32 v0, v0, v2
	v_add_f32_e32 v202, s0, v0
	s_lshl_b64 s[0:1], s[16:17], 2
	v_readlane_b32 s3, v247, 9
	s_add_u32 s44, s60, s0
	s_addc_u32 s45, s61, s1
	v_cndmask_b32_e64 v0, 0, 1, s[2:3]
	s_mov_b64 s[0:1], -1
	s_and_b64 vcc, exec, s[40:41]
	v_cmp_ne_u32_e64 s[2:3], 1, v0
	s_cbranch_vccz .LBB0_446
	v_writelane_b32 v246, s78, 9
	s_nop 1
	v_writelane_b32 v246, s79, 10
	v_writelane_b32 v246, s76, 1
	s_nop 1
	v_writelane_b32 v246, s77, 2
	v_writelane_b32 v246, s2, 11
	s_and_b64 vcc, exec, s[2:3]
	s_nop 0
	v_writelane_b32 v246, s3, 12
	s_cbranch_vccnz .LBB0_445
	v_readlane_b32 s78, v246, 9
	v_readlane_b32 s79, v246, 10
	s_add_u32 s2, s78, 0x15000000
	s_addc_u32 s3, s79, 0
	s_add_u32 s14, s78, 0x16000000
	s_addc_u32 s15, s79, 0
	s_add_u32 s20, s78, 0x6000300
	s_addc_u32 s28, s79, 0
	s_add_u32 s29, s78, 0x2000000
	s_addc_u32 s33, s79, 0
	s_add_u32 s34, s78, 0x6000400
	s_addc_u32 s35, s79, 0
	s_add_u32 s0, s78, 0x6078300
	s_addc_u32 s1, s79, 0
	s_add_u32 s58, s78, 0x16004000
	s_addc_u32 s59, s79, 0
	v_readlane_b32 s60, v247, 23
	s_branch .LBB0_334
